# W_in epilogue: rstd cached across a workgroup's 3-4 tiles as well (first tile computes, later tiles skip the ssq loads, the vmcnt(0) drain and the shuffles)
# baseline (speedup 1.0000x reference)
;     __device__ __forceinline__ bool next(int i, Unit& u) const { if (i > 0 || j < 0 || j >= 32) return false; u.pm = j; u.pn = 0; return true; }
;   __device__ __forceinline__ bool next(int i,AttnUnit&u)const{ const int v=vcu+(i>>1)*G; if(v>=256)return false; const int s=v&15; u.bh=(G==256)?__builtin_amdgcn_readfirstlane(ORD[2*v+(i&1)]):(v>>4); u.qb=(i&1)?s:31-s; return true; }
;     __host__ __device__ bool next(int i, Unit& u) const {
;         const long L = (long)i * G + c; if (L >= nwg) return false;
;         int wgid = (int)L; { const int q = nwg / NXCD, r = nwg % NXCD, xcd = wgid % NXCD, off = wgid / NXCD; wgid = (xcd < r ? xcd * (q + 1) : r * (q + 1) + (xcd - r) * q) + off; }
;         const int nig = WGM * nN, gid = wgid / nig, fm = gid * WGM, gsz = (nM - fm) < WGM ? (nM - fm) : WGM;
;         u.pm = fm + ((wgid % nig) % gsz); u.pn = (wgid % nig) / gsz; return true;
;     }
.LBB0_369:
	s_add_i32 s101, s101, 1
	s_mov_b32 s32, 0
	v_readlane_b32 s4, v255, 20
	s_mov_b32 s89, s83
	v_readlane_b32 s5, v255, 21
	s_waitcnt lgkmcnt(0)
	s_barrier
	s_mov_b32 s74, s56
	s_mov_b32 s16, s69
	v_readlane_b32 s6, v255, 22
	v_readlane_b32 s7, v255, 23
	s_mov_b64 s[0:1], s[4:5]
	v_mov_b32_e32 v14, v203
	s_cmpk_lt_i32 s89, 0x3c0
	s_cselect_b64 s[4:5], -1, 0
	s_cmpk_gt_i32 s89, 0x3bf
	v_readfirstlane_b32 s17, v14
	s_cbranch_scc1 .LBB0_371
	s_ashr_i32 s0, s89, 31
	s_lshr_b32 s0, s0, 29
	s_add_i32 s0, s89, s0
	s_ashr_i32 s1, s0, 3
	s_and_b32 s0, s0, -8
	s_sub_i32 s0, s89, s0
	s_cmp_lt_i32 s0, 0
	s_movk_i32 s2, 0x79
	s_cselect_b32 s2, s2, 0x78
	s_mul_i32 s0, s0, s2
	s_add_i32 s0, s0, s1
	s_mul_hi_i32 s1, s0, 0x88888889
	s_add_i32 s1, s1, s0
	s_lshr_b32 s2, s1, 31
	s_ashr_i32 s1, s1, 6
	s_add_i32 s1, s1, s2
	s_lshl_b32 s2, s1, 3
	s_mulk_i32 s1, 0x78
	s_sub_i32 s0, s0, s1
	s_bfe_i32 s1, s0, 0x80000
	s_bfe_u32 s1, s1, 0x3000c
	s_add_i32 s1, s0, s1
	s_bfe_i32 s8, s1, 0x80000
	s_and_b32 s1, s1, 0xf8
	s_sub_i32 s0, s0, s1
	s_sext_i32_i16 s9, s8
	s_sext_i32_i8 s0, s0
	s_add_i32 s8, s2, s0
	s_ashr_i32 s10, s9, 3

; #define PG8_STAGE(bufoff, gbase, voff) do { _Pragma("unroll") for (int _i = 0; _i < 2; ++_i) \
;         __builtin_amdgcn_global_load_lds((const unsigned*)((const char*)(gbase) + (voff)[_i]), (PG8_LAS unsigned*)(lds + (bufoff) + ldsw + _i * 8192), 16, 0, 0); } while (0)
; #define PG8_LDA(dst, b, h) do { _Pragma("unroll") for (int m = 0; m < 4; ++m) _Pragma("unroll") for (int k = 0; k < 2; ++k) dst[m][k] = *(const PG8_LAS bf16x8*)(lds + PG8_SA(b, h) + aoff + m * 2048 + k * 1024); } while (0)
; #define PG8_LDB(dst, b, h) do { _Pragma("unroll") for (int n = 0; n < 2; ++n) _Pragma("unroll") for (int k = 0; k < 2; ++k) dst[n][k] = *(const PG8_LAS bf16x8*)(lds + PG8_SB(b, h) + boff + n * 2048 + k * 1024); } while (0)
; #define PG8_MMA(ai, bj, At, Bt) do { __builtin_amdgcn_s_setprio(1); _Pragma("unroll") for (int m = 0; m < 4; ++m) _Pragma("unroll") for (int n = 0; n < 2; ++n) _Pragma("unroll") for (int k = 0; k < 2; ++k) \
;         acc[ai][bj][m][n] = __builtin_amdgcn_mfma_f32_16x16x32_bf16(Bt[n][k], At[m][k], acc[ai][bj][m][n], 0, 0, 0); __builtin_amdgcn_s_setprio(0); } while (0)
; #define PG8_WAIT_V(n) asm volatile("s_waitcnt vmcnt(" #n ")" ::: "memory")
; #define PG8_BAR __builtin_amdgcn_s_barrier()
; template <class Epi, class Sched, bool ALIGN_EPI = false, bool SP2 = false>
; __device__ __forceinline__ void gemm_phase(PG8_LAS unsigned char* lds, const Gemm g, const Sched& S, const Epi& E) {
;     ...
;         for (int t = 0; t < nt; t += 2) {
;             const bool last = (t == nt - 2);
;             const char* a1 = cA + (size_t)(t + 1) * kstep;
;             const char* a2 = last ? nA : cA + (size_t)(t + 2) * kstep; const char* b2 = last ? nB : cB + (size_t)(t + 2) * kstep;
;             const char* a3 = a2 + kstep; const char* b3 = b2 + kstep;
;             if (last && has_next) S.a_ready(nxt);
;             if constexpr (SP2) {
;             PG8_LDB(B0, 0, 0); PG8_LDB(B1, 0, 1); PG8_SCHED; PG8_LDA(At, 0, 0); PG8_STAGE(PG8_SA(1, 1), a1 + hstepA, voffA);
;             PG8_WAIT_V(8); PG8_WAIT_L(0); PG8_BAR; PG8_MMA(0, 0, At, B0); PG8_MMA(0, 1, At, B1); PG8_BAR; PG8_SCHED;
;             PG8_LDA(At, 0, 1); PG8_STAGE(PG8_SB(0, 0), b2, voffB); PG8_STAGE(PG8_SB(0, 1), b2 + hstepB, voffB); PG8_STAGE(PG8_SA(0, 0), a2, voffA);
;             PG8_WAIT_V(8); PG8_WAIT_L(0); PG8_BAR; PG8_MMA(1, 0, At, B0); PG8_MMA(1, 1, At, B1); PG8_BAR; PG8_SCHED;
.LBB0_380:
	v_add_u32_e32 v140, s85, v173
	v_add_u32_e32 v170, s78, v173
	ds_read_b128 v[128:131], v140
	ds_read_b128 v[132:135], v140 offset:1024
	ds_read_b128 v[136:139], v140 offset:2048
	ds_read_b128 v[140:143], v140 offset:3072
	ds_read_b128 v[144:147], v170
	ds_read_b128 v[148:151], v170 offset:1024
	ds_read_b128 v[166:169], v170 offset:2048
	ds_read_b128 v[176:179], v170 offset:3072
	s_add_u32 s2, s12, 0xfffc0080
	s_addc_u32 s14, s13, -1
	s_cmp_eq_u32 s22, 12
	s_cselect_b32 s17, s9, s14
	s_cselect_b32 s16, s11, s2
	s_cselect_b32 s15, s18, s21
	s_cselect_b32 s14, s19, s20
	v_lshl_add_u64 v[170:171], s[12:13], 0, v[164:165]
	s_add_i32 m0, s61, 0xc000
	ds_read_b128 v[180:183], v175
	ds_read_b128 v[184:187], v175 offset:1024
	ds_read_b128 v[188:191], v175 offset:2048
	ds_read_b128 v[204:207], v175 offset:3072
	ds_read_b128 v[208:211], v175 offset:4096
	ds_read_b128 v[218:221], v175 offset:5120
	ds_read_b128 v[222:225], v175 offset:6144
	ds_read_b128 v[226:229], v175 offset:7168
	global_load_lds_dwordx4 v[170:171], off
	v_lshl_add_u64 v[170:171], s[12:13], 0, v[162:163]
	s_add_i32 m0, s61, 0xe000
	s_nop 0
	global_load_lds_dwordx4 v[170:171], off
	s_waitcnt vmcnt(8)
	s_waitcnt lgkmcnt(0)
	s_barrier
	s_waitcnt lgkmcnt(0)
	v_mfma_f32_16x16x32_bf16 v[60:63], v[128:131], v[180:183], v[60:63]
	v_mfma_f32_16x16x32_bf16 v[56:59], v[136:139], v[180:183], v[56:59]
	v_mfma_f32_16x16x32_bf16 v[52:55], v[128:131], v[188:191], v[52:55]
	v_mfma_f32_16x16x32_bf16 v[48:51], v[136:139], v[188:191], v[48:51]
	v_mfma_f32_16x16x32_bf16 v[44:47], v[128:131], v[208:211], v[44:47]
	v_mfma_f32_16x16x32_bf16 v[40:43], v[136:139], v[208:211], v[40:43]
	v_mfma_f32_16x16x32_bf16 v[36:39], v[128:131], v[222:225], v[36:39]
	v_mfma_f32_16x16x32_bf16 v[32:35], v[136:139], v[222:225], v[32:35]
	v_mfma_f32_16x16x32_bf16 v[60:63], v[132:135], v[184:187], v[60:63]
	v_mfma_f32_16x16x32_bf16 v[56:59], v[140:143], v[184:187], v[56:59]
	v_mfma_f32_16x16x32_bf16 v[52:55], v[132:135], v[204:207], v[52:55]
	v_mfma_f32_16x16x32_bf16 v[48:51], v[140:143], v[204:207], v[48:51]
	v_mfma_f32_16x16x32_bf16 v[44:47], v[132:135], v[218:221], v[44:47]
	v_mfma_f32_16x16x32_bf16 v[40:43], v[140:143], v[218:221], v[40:43]
	v_mfma_f32_16x16x32_bf16 v[36:39], v[132:135], v[226:229], v[36:39]
	v_mfma_f32_16x16x32_bf16 v[32:35], v[140:143], v[226:229], v[32:35]
	v_mfma_f32_16x16x32_bf16 v[124:127], v[144:147], v[180:183], v[124:127]
	v_mfma_f32_16x16x32_bf16 v[120:123], v[166:169], v[180:183], v[120:123]
	v_mfma_f32_16x16x32_bf16 v[116:119], v[144:147], v[188:191], v[116:119]
	v_mfma_f32_16x16x32_bf16 v[112:115], v[166:169], v[188:191], v[112:115]
	v_mfma_f32_16x16x32_bf16 v[108:111], v[144:147], v[208:211], v[108:111]
	v_mfma_f32_16x16x32_bf16 v[104:107], v[166:169], v[208:211], v[104:107]
	v_mfma_f32_16x16x32_bf16 v[100:103], v[144:147], v[222:225], v[100:103]
	v_mfma_f32_16x16x32_bf16 v[96:99], v[166:169], v[222:225], v[96:99]
	v_mfma_f32_16x16x32_bf16 v[124:127], v[148:151], v[184:187], v[124:127]
	v_mfma_f32_16x16x32_bf16 v[120:123], v[176:179], v[184:187], v[120:123]
	v_mfma_f32_16x16x32_bf16 v[116:119], v[148:151], v[204:207], v[116:119]
	v_mfma_f32_16x16x32_bf16 v[112:115], v[176:179], v[204:207], v[112:115]
	v_mfma_f32_16x16x32_bf16 v[108:111], v[148:151], v[218:221], v[108:111]
	v_mfma_f32_16x16x32_bf16 v[104:107], v[176:179], v[218:221], v[104:107]
	v_mfma_f32_16x16x32_bf16 v[100:103], v[148:151], v[226:229], v[100:103]
	v_mfma_f32_16x16x32_bf16 v[96:99], v[176:179], v[226:229], v[96:99]
	s_barrier
	s_mov_b32 m0, s70
	v_lshl_add_u64 v[170:171], s[14:15], 0, v[154:155]
	s_add_u32 s24, s14, 0x40000
	ds_read_b128 v[180:183], v175 offset:16384
	ds_read_b128 v[184:187], v175 offset:17408
	ds_read_b128 v[188:191], v175 offset:18432
	ds_read_b128 v[204:207], v175 offset:19456
	ds_read_b128 v[208:211], v175 offset:20480
	ds_read_b128 v[218:221], v175 offset:21504
	ds_read_b128 v[222:225], v175 offset:22528
	ds_read_b128 v[226:229], v175 offset:23552
	global_load_lds_dwordx4 v[170:171], off
	v_lshl_add_u64 v[230:231], s[14:15], 0, v[158:159]
	s_mov_b32 m0, s71
	s_addc_u32 s25, s15, 0
	global_load_lds_dwordx4 v[230:231], off
	v_lshl_add_u64 v[232:233], s[24:25], 0, v[154:155]
	s_mov_b32 m0, s79
	v_lshl_add_u64 v[234:235], s[16:17], 0, v[156:157]
	global_load_lds_dwordx4 v[232:233], off
	v_lshl_add_u64 v[232:233], s[24:25], 0, v[158:159]
	s_mov_b32 m0, s60
	s_nop 0
	global_load_lds_dwordx4 v[232:233], off
	v_lshl_add_u64 v[232:233], s[16:17], 0, v[152:153]
	s_mov_b32 m0, s61
	s_nop 0
	global_load_lds_dwordx4 v[232:233], off
	s_mov_b32 m0, s75
	s_nop 0
	global_load_lds_dwordx4 v[234:235], off
	s_waitcnt vmcnt(8)
	s_waitcnt lgkmcnt(0)
	s_barrier
; #define PG8_STAGE(bufoff, gbase, voff) do { _Pragma("unroll") for (int _i = 0; _i < 2; ++_i) \
;         __builtin_amdgcn_global_load_lds((const unsigned*)((const char*)(gbase) + (voff)[_i]), (PG8_LAS unsigned*)(lds + (bufoff) + ldsw + _i * 8192), 16, 0, 0); } while (0)
; #define PG8_LDA(dst, b, h) do { _Pragma("unroll") for (int m = 0; m < 4; ++m) _Pragma("unroll") for (int k = 0; k < 2; ++k) dst[m][k] = *(const PG8_LAS bf16x8*)(lds + PG8_SA(b, h) + aoff + m * 2048 + k * 1024); } while (0)
; #define PG8_LDB(dst, b, h) do { _Pragma("unroll") for (int n = 0; n < 2; ++n) _Pragma("unroll") for (int k = 0; k < 2; ++k) dst[n][k] = *(const PG8_LAS bf16x8*)(lds + PG8_SB(b, h) + boff + n * 2048 + k * 1024); } while (0)
; #define PG8_MMA(ai, bj, At, Bt) do { __builtin_amdgcn_s_setprio(1); _Pragma("unroll") for (int m = 0; m < 4; ++m) _Pragma("unroll") for (int n = 0; n < 2; ++n) _Pragma("unroll") for (int k = 0; k < 2; ++k) \
;         acc[ai][bj][m][n] = __builtin_amdgcn_mfma_f32_16x16x32_bf16(Bt[n][k], At[m][k], acc[ai][bj][m][n], 0, 0, 0); __builtin_amdgcn_s_setprio(0); } while (0)
; #define PG8_WAIT_V(n) asm volatile("s_waitcnt vmcnt(" #n ")" ::: "memory")
; #define PG8_WAIT_L(n) asm volatile("s_waitcnt lgkmcnt(" #n ")" ::: "memory")
; #define PG8_BAR __builtin_amdgcn_s_barrier()
; #define PG8_SCHED __builtin_amdgcn_sched_barrier(0)
; template <class Epi, class Sched, bool ALIGN_EPI = false, bool SP2 = false>
; __device__ __forceinline__ void gemm_phase(PG8_LAS unsigned char* lds, const Gemm g, const Sched& S, const Epi& E) {
;     ...
;             PG8_WAIT_V(8); PG8_WAIT_L(0); PG8_BAR; PG8_MMA(0, 0, At, B0); PG8_MMA(0, 1, At, B1); PG8_BAR; PG8_SCHED;
;             PG8_LDA(At, 0, 1); PG8_STAGE(PG8_SB(0, 0), b2, voffB); PG8_STAGE(PG8_SB(0, 1), b2 + hstepB, voffB); PG8_STAGE(PG8_SA(0, 0), a2, voffA);
;             PG8_WAIT_V(8); PG8_WAIT_L(0); PG8_BAR; PG8_MMA(1, 0, At, B0); PG8_MMA(1, 1, At, B1); PG8_BAR; PG8_SCHED;
;             PG8_LDB(B0, 1, 0); PG8_LDB(B1, 1, 1); PG8_SCHED; PG8_LDA(At, 1, 0); PG8_STAGE(PG8_SA(0, 1), a2 + hstepA, voffA);
;             PG8_WAIT_V(8); PG8_WAIT_L(0); PG8_BAR; PG8_MMA(0, 0, At, B0); PG8_MMA(0, 1, At, B1); PG8_BAR; PG8_SCHED;
	s_waitcnt lgkmcnt(0)
	v_mfma_f32_16x16x32_bf16 v[28:31], v[128:131], v[180:183], v[28:31]
	v_mfma_f32_16x16x32_bf16 v[24:27], v[136:139], v[180:183], v[24:27]
	v_mfma_f32_16x16x32_bf16 v[20:23], v[128:131], v[188:191], v[20:23]
	v_mfma_f32_16x16x32_bf16 v[16:19], v[136:139], v[188:191], v[16:19]
	v_mfma_f32_16x16x32_bf16 v[12:15], v[128:131], v[208:211], v[12:15]
	v_mfma_f32_16x16x32_bf16 v[8:11], v[136:139], v[208:211], v[8:11]
	v_mfma_f32_16x16x32_bf16 v[4:7], v[128:131], v[222:225], v[4:7]
	v_mfma_f32_16x16x32_bf16 v[0:3], v[136:139], v[222:225], v[0:3]
	v_mfma_f32_16x16x32_bf16 v[28:31], v[132:135], v[184:187], v[28:31]
	v_mfma_f32_16x16x32_bf16 v[24:27], v[140:143], v[184:187], v[24:27]
	v_mfma_f32_16x16x32_bf16 v[20:23], v[132:135], v[204:207], v[20:23]
	v_mfma_f32_16x16x32_bf16 v[16:19], v[140:143], v[204:207], v[16:19]
	v_mfma_f32_16x16x32_bf16 v[12:15], v[132:135], v[218:221], v[12:15]
	v_mfma_f32_16x16x32_bf16 v[8:11], v[140:143], v[218:221], v[8:11]
	v_mfma_f32_16x16x32_bf16 v[4:7], v[132:135], v[226:229], v[4:7]
	v_mfma_f32_16x16x32_bf16 v[0:3], v[140:143], v[226:229], v[0:3]
	v_mfma_f32_16x16x32_bf16 v[92:95], v[144:147], v[180:183], v[92:95]
	v_mfma_f32_16x16x32_bf16 v[88:91], v[166:169], v[180:183], v[88:91]
	v_mfma_f32_16x16x32_bf16 v[84:87], v[144:147], v[188:191], v[84:87]
	v_mfma_f32_16x16x32_bf16 v[80:83], v[166:169], v[188:191], v[80:83]
	v_mfma_f32_16x16x32_bf16 v[76:79], v[144:147], v[208:211], v[76:79]
	v_mfma_f32_16x16x32_bf16 v[72:75], v[166:169], v[208:211], v[72:75]
	v_mfma_f32_16x16x32_bf16 v[68:71], v[144:147], v[222:225], v[68:71]
	v_mfma_f32_16x16x32_bf16 v[64:67], v[166:169], v[222:225], v[64:67]
	v_mfma_f32_16x16x32_bf16 v[92:95], v[148:151], v[184:187], v[92:95]
	v_mfma_f32_16x16x32_bf16 v[88:91], v[176:179], v[184:187], v[88:91]
	v_mfma_f32_16x16x32_bf16 v[84:87], v[148:151], v[204:207], v[84:87]
	v_mfma_f32_16x16x32_bf16 v[80:83], v[176:179], v[204:207], v[80:83]
	v_mfma_f32_16x16x32_bf16 v[76:79], v[148:151], v[218:221], v[76:79]
	v_mfma_f32_16x16x32_bf16 v[72:75], v[176:179], v[218:221], v[72:75]
	v_mfma_f32_16x16x32_bf16 v[68:71], v[148:151], v[226:229], v[68:71]
	v_mfma_f32_16x16x32_bf16 v[64:67], v[176:179], v[226:229], v[64:67]
	s_barrier
	v_add_u32_e32 v140, s68, v173
	v_add_u32_e32 v176, s1, v173
	ds_read_b128 v[128:131], v140
	ds_read_b128 v[132:135], v140 offset:1024
	ds_read_b128 v[136:139], v140 offset:2048
	ds_read_b128 v[140:143], v140 offset:3072
	ds_read_b128 v[144:147], v176
	ds_read_b128 v[148:151], v176 offset:1024
	ds_read_b128 v[166:169], v176 offset:2048
	ds_read_b128 v[176:179], v176 offset:3072
	s_add_u32 s16, s16, 0x40000
	s_addc_u32 s17, s17, 0
	s_mov_b32 m0, s4
	v_lshl_add_u64 v[236:237], s[16:17], 0, v[152:153]
	ds_read_b128 v[180:183], v175 offset:32768
	ds_read_b128 v[184:187], v175 offset:33792
	ds_read_b128 v[188:191], v175 offset:34816
	ds_read_b128 v[204:207], v175 offset:35840
	ds_read_b128 v[208:211], v175 offset:36864
	ds_read_b128 v[218:221], v175 offset:37888
	ds_read_b128 v[222:225], v175 offset:38912
	ds_read_b128 v[226:229], v175 offset:39936
	global_load_lds_dwordx4 v[236:237], off
	v_lshl_add_u64 v[236:237], s[16:17], 0, v[156:157]
	s_mov_b32 m0, s5
	s_nop 0
	global_load_lds_dwordx4 v[236:237], off
	s_waitcnt vmcnt(8)
	s_waitcnt lgkmcnt(0)
	s_barrier
	s_waitcnt lgkmcnt(0)
	v_mfma_f32_16x16x32_bf16 v[60:63], v[128:131], v[180:183], v[60:63]
	v_mfma_f32_16x16x32_bf16 v[56:59], v[136:139], v[180:183], v[56:59]
	v_mfma_f32_16x16x32_bf16 v[52:55], v[128:131], v[188:191], v[52:55]
	v_mfma_f32_16x16x32_bf16 v[48:51], v[136:139], v[188:191], v[48:51]
	v_mfma_f32_16x16x32_bf16 v[44:47], v[128:131], v[208:211], v[44:47]
	v_mfma_f32_16x16x32_bf16 v[40:43], v[136:139], v[208:211], v[40:43]
	v_mfma_f32_16x16x32_bf16 v[36:39], v[128:131], v[222:225], v[36:39]
	v_mfma_f32_16x16x32_bf16 v[32:35], v[136:139], v[222:225], v[32:35]
	v_mfma_f32_16x16x32_bf16 v[60:63], v[132:135], v[184:187], v[60:63]
	v_mfma_f32_16x16x32_bf16 v[56:59], v[140:143], v[184:187], v[56:59]
	v_mfma_f32_16x16x32_bf16 v[52:55], v[132:135], v[204:207], v[52:55]
	v_mfma_f32_16x16x32_bf16 v[48:51], v[140:143], v[204:207], v[48:51]
	v_mfma_f32_16x16x32_bf16 v[44:47], v[132:135], v[218:221], v[44:47]
	v_mfma_f32_16x16x32_bf16 v[40:43], v[140:143], v[218:221], v[40:43]
	v_mfma_f32_16x16x32_bf16 v[36:39], v[132:135], v[226:229], v[36:39]
	v_mfma_f32_16x16x32_bf16 v[32:35], v[140:143], v[226:229], v[32:35]
	v_mfma_f32_16x16x32_bf16 v[124:127], v[144:147], v[180:183], v[124:127]
	v_mfma_f32_16x16x32_bf16 v[120:123], v[166:169], v[180:183], v[120:123]
	v_mfma_f32_16x16x32_bf16 v[116:119], v[144:147], v[188:191], v[116:119]
	v_mfma_f32_16x16x32_bf16 v[112:115], v[166:169], v[188:191], v[112:115]
	v_mfma_f32_16x16x32_bf16 v[108:111], v[144:147], v[208:211], v[108:111]
	v_mfma_f32_16x16x32_bf16 v[104:107], v[166:169], v[208:211], v[104:107]
	v_mfma_f32_16x16x32_bf16 v[100:103], v[144:147], v[222:225], v[100:103]
	v_mfma_f32_16x16x32_bf16 v[96:99], v[166:169], v[222:225], v[96:99]
	v_mfma_f32_16x16x32_bf16 v[124:127], v[148:151], v[184:187], v[124:127]
	v_mfma_f32_16x16x32_bf16 v[120:123], v[176:179], v[184:187], v[120:123]
	v_mfma_f32_16x16x32_bf16 v[116:119], v[148:151], v[204:207], v[116:119]
	v_mfma_f32_16x16x32_bf16 v[112:115], v[176:179], v[204:207], v[112:115]
	v_mfma_f32_16x16x32_bf16 v[108:111], v[148:151], v[218:221], v[108:111]
	v_mfma_f32_16x16x32_bf16 v[104:107], v[176:179], v[218:221], v[104:107]
	v_mfma_f32_16x16x32_bf16 v[100:103], v[148:151], v[226:229], v[100:103]
	v_mfma_f32_16x16x32_bf16 v[96:99], v[176:179], v[226:229], v[96:99]
	s_barrier
; #define PG8_STAGE(bufoff, gbase, voff) do { _Pragma("unroll") for (int _i = 0; _i < 2; ++_i) \
;         __builtin_amdgcn_global_load_lds((const unsigned*)((const char*)(gbase) + (voff)[_i]), (PG8_LAS unsigned*)(lds + (bufoff) + ldsw + _i * 8192), 16, 0, 0); } while (0)
; #define PG8_LDA(dst, b, h) do { _Pragma("unroll") for (int m = 0; m < 4; ++m) _Pragma("unroll") for (int k = 0; k < 2; ++k) dst[m][k] = *(const PG8_LAS bf16x8*)(lds + PG8_SA(b, h) + aoff + m * 2048 + k * 1024); } while (0)
; #define PG8_MMA(ai, bj, At, Bt) do { __builtin_amdgcn_s_setprio(1); _Pragma("unroll") for (int m = 0; m < 4; ++m) _Pragma("unroll") for (int n = 0; n < 2; ++n) _Pragma("unroll") for (int k = 0; k < 2; ++k) \
;         acc[ai][bj][m][n] = __builtin_amdgcn_mfma_f32_16x16x32_bf16(Bt[n][k], At[m][k], acc[ai][bj][m][n], 0, 0, 0); __builtin_amdgcn_s_setprio(0); } while (0)
; #define PG8_WAIT_V(n) asm volatile("s_waitcnt vmcnt(" #n ")" ::: "memory")
; #define PG8_WAIT_L(n) asm volatile("s_waitcnt lgkmcnt(" #n ")" ::: "memory")
; #define PG8_BAR __builtin_amdgcn_s_barrier()
; #define PG8_SCHED __builtin_amdgcn_sched_barrier(0)
; template <class Epi, class Sched, bool ALIGN_EPI = false, bool SP2 = false>
; __device__ __forceinline__ void gemm_phase(PG8_LAS unsigned char* lds, const Gemm g, const Sched& S, const Epi& E) {
;     ...
;             PG8_WAIT_V(8); PG8_WAIT_L(0); PG8_BAR; PG8_MMA(0, 0, At, B0); PG8_MMA(0, 1, At, B1); PG8_BAR; PG8_SCHED;
;             PG8_LDA(At, 1, 1); PG8_STAGE(PG8_SB(1, 0), b3, voffB); PG8_STAGE(PG8_SB(1, 1), b3 + hstepB, voffB); PG8_STAGE(PG8_SA(1, 0), a3, voffA);
;             PG8_WAIT_V(8); PG8_WAIT_L(0); PG8_BAR; PG8_MMA(1, 0, At, B0); PG8_MMA(1, 1, At, B1); PG8_BAR; PG8_SCHED;
; __device__ __forceinline__ float row_rstd(const float* ssq, int row, int fq) {
;     const f32x4 v = *(const f32x4*)(ssq + (size_t)row * 16 + fq * 4);
;     float s = (v[0] + v[1]) + (v[2] + v[3]);
;     s += __shfl_xor(s, 16); s += __shfl_xor(s, 32);
;     return __builtin_amdgcn_rsqf(s * (1.f / DM) + EPS);
	s_mov_b32 m0, s84
	v_lshl_add_u64 v[170:171], v[170:171], 0, s[76:77]
	s_add_u32 s14, s14, 0x40080
	ds_read_b128 v[180:183], v175 offset:49152
	ds_read_b128 v[184:187], v175 offset:50176
	ds_read_b128 v[188:191], v175 offset:51200
	ds_read_b128 v[204:207], v175 offset:52224
	ds_read_b128 v[208:211], v175 offset:53248
	ds_read_b128 v[218:221], v175 offset:54272
	ds_read_b128 v[222:225], v175 offset:55296
	ds_read_b128 v[226:229], v175 offset:56320
	global_load_lds_dwordx4 v[170:171], off
	v_lshl_add_u64 v[170:171], v[230:231], 0, s[76:77]
	s_mov_b32 m0, s64
	s_addc_u32 s15, s15, 0
	global_load_lds_dwordx4 v[170:171], off
	v_lshl_add_u64 v[170:171], s[14:15], 0, v[154:155]
	s_mov_b32 m0, s48
	s_nop 0
	global_load_lds_dwordx4 v[170:171], off
	v_lshl_add_u64 v[170:171], s[14:15], 0, v[158:159]
	s_mov_b32 m0, s49
	s_nop 0
	global_load_lds_dwordx4 v[170:171], off
	v_lshl_add_u64 v[170:171], v[232:233], 0, s[76:77]
	s_mov_b32 m0, s65
	s_nop 0
	global_load_lds_dwordx4 v[170:171], off
	v_lshl_add_u64 v[170:171], v[234:235], 0, s[76:77]
	s_mov_b32 m0, s0
	s_nop 0
	global_load_lds_dwordx4 v[170:171], off
	s_waitcnt vmcnt(8)
	s_waitcnt lgkmcnt(0)
	s_barrier
	s_waitcnt lgkmcnt(0)
	v_mfma_f32_16x16x32_bf16 v[28:31], v[128:131], v[180:183], v[28:31]
	v_mfma_f32_16x16x32_bf16 v[24:27], v[136:139], v[180:183], v[24:27]
	v_mfma_f32_16x16x32_bf16 v[20:23], v[128:131], v[188:191], v[20:23]
	v_mfma_f32_16x16x32_bf16 v[16:19], v[136:139], v[188:191], v[16:19]
	v_mfma_f32_16x16x32_bf16 v[12:15], v[128:131], v[208:211], v[12:15]
	v_mfma_f32_16x16x32_bf16 v[8:11], v[136:139], v[208:211], v[8:11]
	v_mfma_f32_16x16x32_bf16 v[4:7], v[128:131], v[222:225], v[4:7]
	v_mfma_f32_16x16x32_bf16 v[0:3], v[136:139], v[222:225], v[0:3]
	v_mfma_f32_16x16x32_bf16 v[28:31], v[132:135], v[184:187], v[28:31]
	v_mfma_f32_16x16x32_bf16 v[24:27], v[140:143], v[184:187], v[24:27]
	v_mfma_f32_16x16x32_bf16 v[20:23], v[132:135], v[204:207], v[20:23]
	v_mfma_f32_16x16x32_bf16 v[16:19], v[140:143], v[204:207], v[16:19]
	v_mfma_f32_16x16x32_bf16 v[12:15], v[132:135], v[218:221], v[12:15]
	v_mfma_f32_16x16x32_bf16 v[8:11], v[140:143], v[218:221], v[8:11]
	v_mfma_f32_16x16x32_bf16 v[4:7], v[132:135], v[226:229], v[4:7]
	v_mfma_f32_16x16x32_bf16 v[0:3], v[140:143], v[226:229], v[0:3]
	v_mfma_f32_16x16x32_bf16 v[92:95], v[144:147], v[180:183], v[92:95]
	v_mfma_f32_16x16x32_bf16 v[88:91], v[166:169], v[180:183], v[88:91]
	v_mfma_f32_16x16x32_bf16 v[84:87], v[144:147], v[188:191], v[84:87]
	v_mfma_f32_16x16x32_bf16 v[80:83], v[166:169], v[188:191], v[80:83]
	v_mfma_f32_16x16x32_bf16 v[76:79], v[144:147], v[208:211], v[76:79]
	v_mfma_f32_16x16x32_bf16 v[72:75], v[166:169], v[208:211], v[72:75]
	v_mfma_f32_16x16x32_bf16 v[68:71], v[144:147], v[222:225], v[68:71]
	v_mfma_f32_16x16x32_bf16 v[64:67], v[166:169], v[222:225], v[64:67]
	v_mfma_f32_16x16x32_bf16 v[92:95], v[148:151], v[184:187], v[92:95]
	v_mfma_f32_16x16x32_bf16 v[88:91], v[176:179], v[184:187], v[88:91]
	v_mfma_f32_16x16x32_bf16 v[84:87], v[148:151], v[204:207], v[84:87]
	v_mfma_f32_16x16x32_bf16 v[80:83], v[176:179], v[204:207], v[80:83]
	v_mfma_f32_16x16x32_bf16 v[76:79], v[148:151], v[218:221], v[76:79]
	v_mfma_f32_16x16x32_bf16 v[72:75], v[176:179], v[218:221], v[72:75]
	v_mfma_f32_16x16x32_bf16 v[68:71], v[148:151], v[226:229], v[68:71]
	v_mfma_f32_16x16x32_bf16 v[64:67], v[176:179], v[226:229], v[64:67]
	s_barrier
	s_add_i32 s22, s22, 2
	s_add_u32 s20, s20, 0x100
	s_addc_u32 s21, s21, 0
	s_add_u32 s12, s12, 0x100
	s_addc_u32 s13, s13, 0
	s_cmp_gt_u32 s22, 13
	s_cbranch_scc0 .LBB0_380
	s_cmp_eq_u32 s10, 14
	s_cbranch_scc1 .Lewh_skip
	s_cmp_lg_u32 s32, 0
	s_cbranch_scc1 .Lewh_skip
	v_lshl_add_u32 v214, s8, 8, v172
	v_mov_b32_e32 v128, v214
	v_ashrrev_i32_e32 v129, 31, v128
	v_lshlrev_b64 v[128:129], 6, v[128:129]
	v_lshl_add_u64 v[128:129], v[160:161], 0, v[128:129]
	global_load_dwordx4 v[128:131], v[128:129], off
	v_add_u32_e32 v132, 16, v214
	v_ashrrev_i32_e32 v133, 31, v132
	v_lshlrev_b64 v[132:133], 6, v[132:133]
	v_lshl_add_u64 v[132:133], v[160:161], 0, v[132:133]
	global_load_dwordx4 v[132:135], v[132:133], off
	v_add_u32_e32 v136, 32, v214
	v_ashrrev_i32_e32 v137, 31, v136
	v_lshlrev_b64 v[136:137], 6, v[136:137]
	v_lshl_add_u64 v[136:137], v[160:161], 0, v[136:137]
	global_load_dwordx4 v[136:139], v[136:137], off
	v_add_u32_e32 v140, 48, v214
	v_ashrrev_i32_e32 v141, 31, v140
	v_lshlrev_b64 v[140:141], 6, v[140:141]
	v_lshl_add_u64 v[140:141], v[160:161], 0, v[140:141]
	global_load_dwordx4 v[140:143], v[140:141], off
	v_add_u32_e32 v144, 0x80, v214
	v_ashrrev_i32_e32 v145, 31, v144
	v_lshlrev_b64 v[144:145], 6, v[144:145]
	v_lshl_add_u64 v[144:145], v[160:161], 0, v[144:145]
	global_load_dwordx4 v[144:147], v[144:145], off
	v_add_u32_e32 v148, 0x90, v214
	v_ashrrev_i32_e32 v149, 31, v148
	v_lshlrev_b64 v[148:149], 6, v[148:149]
	v_lshl_add_u64 v[148:149], v[160:161], 0, v[148:149]
	global_load_dwordx4 v[148:151], v[148:149], off
	v_add_u32_e32 v236, 0xa0, v214
	v_ashrrev_i32_e32 v237, 31, v236
	v_lshlrev_b64 v[236:237], 6, v[236:237]
	v_lshl_add_u64 v[236:237], v[160:161], 0, v[236:237]
	global_load_dwordx4 v[236:239], v[236:237], off
	v_add_u32_e32 v246, 0xb0, v214
	v_ashrrev_i32_e32 v247, 31, v246
	v_lshlrev_b64 v[246:247], 6, v[246:247]
	v_lshl_add_u64 v[246:247], v[160:161], 0, v[246:247]
	global_load_dwordx4 v[246:249], v[246:247], off

; __device__ __forceinline__ float silu_f(float x) { return x * __builtin_amdgcn_rcpf(1.f + __expf(-x)); }
; __device__ __forceinline__ v4u pack8(const f32x4 a, const f32x4 b) { v4u w; w.x = cvt_pk_bf16(a[0], a[1]); w.y = cvt_pk_bf16(a[2], a[3]); w.z = cvt_pk_bf16(b[0], b[1]); w.w = cvt_pk_bf16(b[2], b[3]); return w; }
; __device__ __forceinline__ float row_rstd(const float* ssq, int row, int fq) {
;     const f32x4 v = *(const f32x4*)(ssq + (size_t)row * 16 + fq * 4);
;     float s = (v[0] + v[1]) + (v[2] + v[3]);
;     s += __shfl_xor(s, 16); s += __shfl_xor(s, 32);
;     return __builtin_amdgcn_rsqf(s * (1.f / DM) + EPS);
;     __device__ __forceinline__ void operator()(const f32x4 (&acc)[2][2][4][2], const pg8::Unit& u, int wr, int wc, int fr, int fq) const {
;     ...
;         const int grp = pn >> 1, cb = (pn & 1) * 256 + cw;
;     ...
;         if (grp == 0) { WIN_LOOP( _Pragma("unroll") for (int i = 0; i < 4; ++i) { a[i] = silu_f(a[i]); b[i] = silu_f(b[i]); } *(v4u*)(QO + (size_t)row * DM + c) = pack8(a, b); ) }
;         else if (grp == 3) { WIN_LOOP( _Pragma("unroll") for (int i = 0; i < 4; ++i) { a[i] = silu_f(a[i]); b[i] = silu_f(b[i]); } *(v4u*)(GH + (size_t)row * 512 + c) = pack8(a, b); ) }
;         else if (grp == 1) {
;             f32x4 l0[2], l1[2];
; #pragma unroll
;             for (int bj = 0; bj < 2; ++bj) { l0[bj] = *(const f32x4*)(lb + cb + bj * 128); l1[bj] = *(const f32x4*)(lb + cb + bj * 128 + 4); }
;             WIN_LOOP( _Pragma("unroll") for (int i = 0; i < 4; ++i) { const float s0 = fminf(a[i], 0.f) - __logf(1.f + __expf(-fabsf(a[i]))), s1 = fminf(b[i], 0.f) - __logf(1.f + __expf(-fabsf(b[i]))); const float la = l0[bj][i], lbv = l1[bj][i];
;                     a[i] = la > 0.f ? __logf(la + (1.f - la) * __expf(s0)) : s0; b[i] = lbv > 0.f ? __logf(lbv + (1.f - lbv) * __expf(s1)) : s1; }
;                 *(f32x4*)(LF + (size_t)row * 512 + c) = a; *(f32x4*)(LF + (size_t)row * 512 + c + 4) = b; __builtin_amdgcn_sched_barrier(0); ) }
;         else if (grp == 2) { WIN_LOOP( *(v4u*)(VH + (size_t)row * 512 + c) = pack8(a, b); ) }
;         else if (grp == 4) { WIN_LOOP( *(v4u*)(QO + (size_t)row * DM + 512 + c) = pack8(a * C2Q, b * C2Q); ) }
;         else if (grp == 5) { WIN_LOOP( *(v4u*)(FK + (size_t)row * 512 + c) = pack8(a, b); ) }
.LBB0_394:
	s_cmp_lg_u32 s32, 0
	s_cbranch_scc1 .Lewr_skip
	s_waitcnt vmcnt(0)
	v_add_f32_e32 v128, v128, v129
	v_add_f32_e32 v130, v130, v131
	v_add_f32_e32 v132, v132, v133
	v_add_f32_e32 v134, v134, v135
	v_add_f32_e32 v136, v136, v137
	v_add_f32_e32 v138, v138, v139
	v_add_f32_e32 v140, v140, v141
	v_add_f32_e32 v142, v142, v143
	v_add_f32_e32 v144, v144, v145
	v_add_f32_e32 v146, v146, v147
	v_add_f32_e32 v148, v148, v149
	v_add_f32_e32 v150, v150, v151
	v_add_f32_e32 v236, v236, v237
	v_add_f32_e32 v238, v238, v239
	v_add_f32_e32 v246, v246, v247
	v_add_f32_e32 v248, v248, v249
	v_add_f32_e32 v128, v128, v130
	v_add_f32_e32 v132, v132, v134
	v_add_f32_e32 v136, v136, v138
	v_add_f32_e32 v140, v140, v142
	v_add_f32_e32 v144, v144, v146
	v_add_f32_e32 v148, v148, v150
	v_add_f32_e32 v236, v236, v238
	v_add_f32_e32 v246, v246, v248
	v_xor_b32_e32 v130, 16, v215
	v_xor_b32_e32 v131, 32, v215
	v_lshlrev_b32_e32 v130, 2, v130
	v_lshlrev_b32_e32 v131, 2, v131
	ds_bpermute_b32 v129, v130, v128
	ds_bpermute_b32 v133, v130, v132
	ds_bpermute_b32 v137, v130, v136
	ds_bpermute_b32 v141, v130, v140
	ds_bpermute_b32 v145, v130, v144
	ds_bpermute_b32 v149, v130, v148
	ds_bpermute_b32 v237, v130, v236
	ds_bpermute_b32 v247, v130, v246
	s_waitcnt lgkmcnt(0)
	v_add_f32_e32 v128, v128, v129
	v_add_f32_e32 v132, v132, v133
	v_add_f32_e32 v136, v136, v137
	v_add_f32_e32 v140, v140, v141
	v_add_f32_e32 v144, v144, v145
	v_add_f32_e32 v148, v148, v149
	v_add_f32_e32 v236, v236, v237
	v_add_f32_e32 v246, v246, v247
	ds_bpermute_b32 v129, v131, v128
	ds_bpermute_b32 v133, v131, v132
	ds_bpermute_b32 v137, v131, v136
	ds_bpermute_b32 v141, v131, v140
	ds_bpermute_b32 v145, v131, v144
	ds_bpermute_b32 v149, v131, v148
	ds_bpermute_b32 v237, v131, v236
	ds_bpermute_b32 v247, v131, v246
	s_waitcnt lgkmcnt(0)
	v_add_f32_e32 v128, v128, v129
	v_add_f32_e32 v132, v132, v133
	v_add_f32_e32 v136, v136, v137
	v_add_f32_e32 v140, v140, v141
	v_add_f32_e32 v144, v144, v145
	v_add_f32_e32 v148, v148, v149
	v_add_f32_e32 v236, v236, v237
	v_add_f32_e32 v246, v246, v247
	v_fmamk_f32 v128, v128, 0x3a800000, v212
	v_fmamk_f32 v132, v132, 0x3a800000, v212
	v_fmamk_f32 v136, v136, 0x3a800000, v212
	v_fmamk_f32 v140, v140, 0x3a800000, v212
	v_fmamk_f32 v144, v144, 0x3a800000, v212
	v_fmamk_f32 v148, v148, 0x3a800000, v212
	v_fmamk_f32 v236, v236, 0x3a800000, v212
	v_fmamk_f32 v246, v246, 0x3a800000, v212
	v_rsq_f32_e32 v250, v128
	v_rsq_f32_e32 v251, v132
	v_rsq_f32_e32 v252, v136
	v_rsq_f32_e32 v253, v140
	v_rsq_f32_e32 v254, v144
	v_rsq_f32_e32 v240, v148
	v_rsq_f32_e32 v241, v236
	v_rsq_f32_e32 v245, v246
	s_nop 0
	s_mov_b32 s32, 1
.Lewr_skip:
	s_lshl_b32 s8, s2, 8
	s_and_b32 s8, s8, 0x100
	v_or_b32_e32 v176, s8, v174
	s_cmp_gt_u32 s2, 1
	s_mov_b64 s[8:9], -1
	s_cbranch_scc0 .LBB0_417
	s_ashr_i32 s14, s2, 1
	s_mov_b64 s[12:13], -1
	s_mov_b64 s[8:9], 0
	s_cmp_lt_i32 s14, 3
	s_mov_b64 s[10:11], 0
	s_cbranch_scc1 .LBB0_407
	s_cmp_gt_i32 s14, 3
	s_cbranch_scc0 .LBB0_404
	s_cmp_gt_i32 s14, 4
	s_cbranch_scc0 .LBB0_401
	s_cmp_eq_u32 s14, 5
	s_mov_b64 s[10:11], -1
	s_cbranch_scc0 .LBB0_400
	v_and_b32_e32 v129, 64, v215
	v_xor_b32_e32 v128, 16, v215
	v_add_u32_e32 v129, 64, v129
	v_cmp_lt_i32_e32 vcc, v128, v129
	v_ashrrev_i32_e32 v167, 31, v166
	v_readlane_b32 s10, v255, 41
	v_cndmask_b32_e32 v128, v215, v128, vcc
	v_lshlrev_b32_e32 v130, 2, v128
	v_xor_b32_e32 v128, 32, v215
	v_cmp_lt_i32_e32 vcc, v128, v129
	v_readlane_b32 s11, v255, 42
	v_lshlrev_b32_e32 v192, 1, v176
	v_cndmask_b32_e32 v128, v215, v128, vcc
	v_lshlrev_b32_e32 v131, 2, v128
	v_lshlrev_b64 v[128:129], 6, v[166:167]
	v_lshl_add_u64 v[128:129], v[160:161], 0, v[128:129]
	s_nop 0
	s_waitcnt lgkmcnt(0)
	s_nop 3
	v_lshlrev_b64 v[132:133], 10, v[166:167]
	s_nop 1
	v_lshl_add_u64 v[136:137], s[10:11], 0, v[132:133]
	v_lshl_add_u64 v[136:137], v[136:137], 0, v[192:193]
	s_waitcnt lgkmcnt(0)
	s_nop 1
	s_waitcnt lgkmcnt(0)
	s_nop 1
	v_mov_b32_e32 v128, v250
	s_nop 0
	v_pk_mul_f32 v[134:135], v[62:63], v[128:129] op_sel_hi:[1,0]
	v_pk_mul_f32 v[132:133], v[60:61], v[128:129] op_sel_hi:[1,0]
	v_pk_mul_f32 v[138:139], v[58:59], v[128:129] op_sel_hi:[1,0]
	v_pk_mul_f32 v[140:141], v[56:57], v[128:129] op_sel_hi:[1,0]
	v_cvt_pk_bf16_f32 v132, v132, v133
	v_cvt_pk_bf16_f32 v133, v134, v135
	v_cvt_pk_bf16_f32 v134, v140, v141
	v_cvt_pk_bf16_f32 v135, v138, v139
	global_store_dwordx4 v[136:137], v[132:135], off
	v_pk_mul_f32 v[138:139], v[122:123], v[128:129] op_sel_hi:[1,0]
	s_nop 0
	v_pk_mul_f32 v[134:135], v[126:127], v[128:129] op_sel_hi:[1,0]
	v_pk_mul_f32 v[132:133], v[124:125], v[128:129] op_sel_hi:[1,0]
	v_pk_mul_f32 v[128:129], v[120:121], v[128:129] op_sel_hi:[1,0]
	v_cvt_pk_bf16_f32 v132, v132, v133
	v_cvt_pk_bf16_f32 v133, v134, v135
	v_cvt_pk_bf16_f32 v134, v128, v129
	v_or_b32_e32 v128, 16, v166
	v_cvt_pk_bf16_f32 v135, v138, v139
	v_ashrrev_i32_e32 v129, 31, v128
	global_store_dwordx4 v[136:137], v[132:135], off offset:256
	s_nop 1
	v_lshlrev_b64 v[132:133], 6, v[128:129]
	v_lshl_add_u64 v[132:133], v[160:161], 0, v[132:133]
	s_nop 0
	v_lshlrev_b64 v[128:129], 10, v[128:129]
	v_lshl_add_u64 v[128:129], s[10:11], 0, v[128:129]
	v_lshl_add_u64 v[128:129], v[128:129], 0, v[192:193]
	s_waitcnt lgkmcnt(0)
	s_nop 3
	s_nop 0
	s_nop 1
	s_waitcnt lgkmcnt(0)
	s_nop 1
	s_waitcnt lgkmcnt(0)
; __device__ __forceinline__ float silu_f(float x) { return x * __builtin_amdgcn_rcpf(1.f + __expf(-x)); }
; __device__ __forceinline__ v4u pack8(const f32x4 a, const f32x4 b) { v4u w; w.x = cvt_pk_bf16(a[0], a[1]); w.y = cvt_pk_bf16(a[2], a[3]); w.z = cvt_pk_bf16(b[0], b[1]); w.w = cvt_pk_bf16(b[2], b[3]); return w; }
;     __device__ __forceinline__ void operator()(const f32x4 (&acc)[2][2][4][2], const pg8::Unit& u, int wr, int wc, int fr, int fq) const {
;     ...
;         if (grp == 0) { WIN_LOOP( _Pragma("unroll") for (int i = 0; i < 4; ++i) { a[i] = silu_f(a[i]); b[i] = silu_f(b[i]); } *(v4u*)(QO + (size_t)row * DM + c) = pack8(a, b); ) }
;         else if (grp == 3) { WIN_LOOP( _Pragma("unroll") for (int i = 0; i < 4; ++i) { a[i] = silu_f(a[i]); b[i] = silu_f(b[i]); } *(v4u*)(GH + (size_t)row * 512 + c) = pack8(a, b); ) }
;         else if (grp == 1) {
;             f32x4 l0[2], l1[2];
; #pragma unroll
;             for (int bj = 0; bj < 2; ++bj) { l0[bj] = *(const f32x4*)(lb + cb + bj * 128); l1[bj] = *(const f32x4*)(lb + cb + bj * 128 + 4); }
;             WIN_LOOP( _Pragma("unroll") for (int i = 0; i < 4; ++i) { const float s0 = fminf(a[i], 0.f) - __logf(1.f + __expf(-fabsf(a[i]))), s1 = fminf(b[i], 0.f) - __logf(1.f + __expf(-fabsf(b[i]))); const float la = l0[bj][i], lbv = l1[bj][i];
;                     a[i] = la > 0.f ? __logf(la + (1.f - la) * __expf(s0)) : s0; b[i] = lbv > 0.f ? __logf(lbv + (1.f - lbv) * __expf(s1)) : s1; }
;                 *(f32x4*)(LF + (size_t)row * 512 + c) = a; *(f32x4*)(LF + (size_t)row * 512 + c + 4) = b; __builtin_amdgcn_sched_barrier(0); ) }
;         else if (grp == 2) { WIN_LOOP( *(v4u*)(VH + (size_t)row * 512 + c) = pack8(a, b); ) }
;         else if (grp == 4) { WIN_LOOP( *(v4u*)(QO + (size_t)row * DM + 512 + c) = pack8(a * C2Q, b * C2Q); ) }
;         else if (grp == 5) { WIN_LOOP( *(v4u*)(FK + (size_t)row * 512 + c) = pack8(a, b); ) }
	s_nop 1
	v_mov_b32_e32 v136, v251
	s_nop 0
	v_pk_mul_f32 v[134:135], v[54:55], v[136:137] op_sel_hi:[1,0]
	v_pk_mul_f32 v[132:133], v[52:53], v[136:137] op_sel_hi:[1,0]
	v_pk_mul_f32 v[138:139], v[50:51], v[136:137] op_sel_hi:[1,0]
	v_pk_mul_f32 v[140:141], v[48:49], v[136:137] op_sel_hi:[1,0]
	v_cvt_pk_bf16_f32 v132, v132, v133
	v_cvt_pk_bf16_f32 v133, v134, v135
	v_cvt_pk_bf16_f32 v134, v140, v141
	v_cvt_pk_bf16_f32 v135, v138, v139
	global_store_dwordx4 v[128:129], v[132:135], off
	v_pk_mul_f32 v[138:139], v[114:115], v[136:137] op_sel_hi:[1,0]
	s_nop 0
	v_pk_mul_f32 v[134:135], v[118:119], v[136:137] op_sel_hi:[1,0]
	v_pk_mul_f32 v[132:133], v[116:117], v[136:137] op_sel_hi:[1,0]
	v_pk_mul_f32 v[136:137], v[112:113], v[136:137] op_sel_hi:[1,0]
	v_cvt_pk_bf16_f32 v132, v132, v133
	v_cvt_pk_bf16_f32 v133, v134, v135
	v_cvt_pk_bf16_f32 v134, v136, v137
	v_cvt_pk_bf16_f32 v135, v138, v139
	global_store_dwordx4 v[128:129], v[132:135], off offset:256
	v_or_b32_e32 v128, 32, v166
	v_ashrrev_i32_e32 v129, 31, v128
	v_lshlrev_b64 v[132:133], 6, v[128:129]
	v_lshl_add_u64 v[132:133], v[160:161], 0, v[132:133]
	s_nop 0
	v_lshlrev_b64 v[128:129], 10, v[128:129]
	v_lshl_add_u64 v[128:129], s[10:11], 0, v[128:129]
	v_lshl_add_u64 v[128:129], v[128:129], 0, v[192:193]
	s_waitcnt lgkmcnt(0)
	s_nop 3
	s_nop 0
	s_nop 1
	s_waitcnt lgkmcnt(0)
	s_nop 1
	s_waitcnt lgkmcnt(0)
	s_nop 1
	v_mov_b32_e32 v136, v252
	s_nop 0
	v_pk_mul_f32 v[134:135], v[46:47], v[136:137] op_sel_hi:[1,0]
	v_pk_mul_f32 v[132:133], v[44:45], v[136:137] op_sel_hi:[1,0]
	v_pk_mul_f32 v[138:139], v[42:43], v[136:137] op_sel_hi:[1,0]
	v_pk_mul_f32 v[140:141], v[40:41], v[136:137] op_sel_hi:[1,0]
	v_cvt_pk_bf16_f32 v132, v132, v133
	v_cvt_pk_bf16_f32 v133, v134, v135
	v_cvt_pk_bf16_f32 v134, v140, v141
	v_cvt_pk_bf16_f32 v135, v138, v139
	global_store_dwordx4 v[128:129], v[132:135], off
	v_pk_mul_f32 v[138:139], v[106:107], v[136:137] op_sel_hi:[1,0]
	s_nop 0
	v_pk_mul_f32 v[134:135], v[110:111], v[136:137] op_sel_hi:[1,0]
	v_pk_mul_f32 v[132:133], v[108:109], v[136:137] op_sel_hi:[1,0]
	v_pk_mul_f32 v[136:137], v[104:105], v[136:137] op_sel_hi:[1,0]
	v_cvt_pk_bf16_f32 v132, v132, v133
	v_cvt_pk_bf16_f32 v133, v134, v135
	v_cvt_pk_bf16_f32 v134, v136, v137
	v_cvt_pk_bf16_f32 v135, v138, v139
	global_store_dwordx4 v[128:129], v[132:135], off offset:256
	v_or_b32_e32 v128, 48, v166
	v_ashrrev_i32_e32 v129, 31, v128
	v_lshlrev_b64 v[132:133], 6, v[128:129]
	v_lshl_add_u64 v[132:133], v[160:161], 0, v[132:133]
	s_nop 0
	v_lshlrev_b64 v[128:129], 10, v[128:129]
	v_lshl_add_u64 v[128:129], s[10:11], 0, v[128:129]
	v_lshl_add_u64 v[128:129], v[128:129], 0, v[192:193]
	s_waitcnt lgkmcnt(0)
	s_nop 3
	s_nop 0
	s_nop 1
	s_waitcnt lgkmcnt(0)
	s_nop 1
	s_waitcnt lgkmcnt(0)
	s_nop 1
	v_mov_b32_e32 v136, v253
	s_nop 0
	v_pk_mul_f32 v[134:135], v[38:39], v[136:137] op_sel_hi:[1,0]
	v_pk_mul_f32 v[132:133], v[36:37], v[136:137] op_sel_hi:[1,0]
	v_pk_mul_f32 v[138:139], v[34:35], v[136:137] op_sel_hi:[1,0]
	v_pk_mul_f32 v[140:141], v[32:33], v[136:137] op_sel_hi:[1,0]
	v_cvt_pk_bf16_f32 v132, v132, v133
	v_cvt_pk_bf16_f32 v133, v134, v135
	v_cvt_pk_bf16_f32 v134, v140, v141
	v_cvt_pk_bf16_f32 v135, v138, v139
	global_store_dwordx4 v[128:129], v[132:135], off
	v_pk_mul_f32 v[138:139], v[98:99], v[136:137] op_sel_hi:[1,0]
	s_nop 0
	v_pk_mul_f32 v[134:135], v[102:103], v[136:137] op_sel_hi:[1,0]
	v_pk_mul_f32 v[132:133], v[100:101], v[136:137] op_sel_hi:[1,0]
	v_pk_mul_f32 v[136:137], v[96:97], v[136:137] op_sel_hi:[1,0]
	v_cvt_pk_bf16_f32 v132, v132, v133
	v_cvt_pk_bf16_f32 v133, v134, v135
	v_cvt_pk_bf16_f32 v134, v136, v137
	v_cvt_pk_bf16_f32 v135, v138, v139
	global_store_dwordx4 v[128:129], v[132:135], off offset:256
	v_add_u32_e32 v128, 0x80, v166
	v_ashrrev_i32_e32 v129, 31, v128
	v_lshlrev_b64 v[132:133], 6, v[128:129]
	v_lshl_add_u64 v[132:133], v[160:161], 0, v[132:133]
	s_nop 0
	v_lshlrev_b64 v[128:129], 10, v[128:129]
	v_lshl_add_u64 v[128:129], s[10:11], 0, v[128:129]
	v_lshl_add_u64 v[128:129], v[128:129], 0, v[192:193]
	s_waitcnt lgkmcnt(0)
	s_nop 3
	s_nop 0
	s_nop 1
	s_waitcnt lgkmcnt(0)
	s_nop 1
	s_waitcnt lgkmcnt(0)
; __device__ __forceinline__ float silu_f(float x) { return x * __builtin_amdgcn_rcpf(1.f + __expf(-x)); }
; __device__ __forceinline__ v4u pack8(const f32x4 a, const f32x4 b) { v4u w; w.x = cvt_pk_bf16(a[0], a[1]); w.y = cvt_pk_bf16(a[2], a[3]); w.z = cvt_pk_bf16(b[0], b[1]); w.w = cvt_pk_bf16(b[2], b[3]); return w; }
;     __device__ __forceinline__ void operator()(const f32x4 (&acc)[2][2][4][2], const pg8::Unit& u, int wr, int wc, int fr, int fq) const {
;     ...
;         if (grp == 0) { WIN_LOOP( _Pragma("unroll") for (int i = 0; i < 4; ++i) { a[i] = silu_f(a[i]); b[i] = silu_f(b[i]); } *(v4u*)(QO + (size_t)row * DM + c) = pack8(a, b); ) }
;         else if (grp == 3) { WIN_LOOP( _Pragma("unroll") for (int i = 0; i < 4; ++i) { a[i] = silu_f(a[i]); b[i] = silu_f(b[i]); } *(v4u*)(GH + (size_t)row * 512 + c) = pack8(a, b); ) }
;         else if (grp == 1) {
;             f32x4 l0[2], l1[2];
; #pragma unroll
;             for (int bj = 0; bj < 2; ++bj) { l0[bj] = *(const f32x4*)(lb + cb + bj * 128); l1[bj] = *(const f32x4*)(lb + cb + bj * 128 + 4); }
;             WIN_LOOP( _Pragma("unroll") for (int i = 0; i < 4; ++i) { const float s0 = fminf(a[i], 0.f) - __logf(1.f + __expf(-fabsf(a[i]))), s1 = fminf(b[i], 0.f) - __logf(1.f + __expf(-fabsf(b[i]))); const float la = l0[bj][i], lbv = l1[bj][i];
;                     a[i] = la > 0.f ? __logf(la + (1.f - la) * __expf(s0)) : s0; b[i] = lbv > 0.f ? __logf(lbv + (1.f - lbv) * __expf(s1)) : s1; }
;                 *(f32x4*)(LF + (size_t)row * 512 + c) = a; *(f32x4*)(LF + (size_t)row * 512 + c + 4) = b; __builtin_amdgcn_sched_barrier(0); ) }
;         else if (grp == 2) { WIN_LOOP( *(v4u*)(VH + (size_t)row * 512 + c) = pack8(a, b); ) }
;         else if (grp == 4) { WIN_LOOP( *(v4u*)(QO + (size_t)row * DM + 512 + c) = pack8(a * C2Q, b * C2Q); ) }
;         else if (grp == 5) { WIN_LOOP( *(v4u*)(FK + (size_t)row * 512 + c) = pack8(a, b); ) }
	s_nop 1
	v_mov_b32_e32 v136, v254
	s_nop 0
	v_pk_mul_f32 v[134:135], v[30:31], v[136:137] op_sel_hi:[1,0]
	v_pk_mul_f32 v[132:133], v[28:29], v[136:137] op_sel_hi:[1,0]
	v_pk_mul_f32 v[138:139], v[26:27], v[136:137] op_sel_hi:[1,0]
	v_pk_mul_f32 v[140:141], v[24:25], v[136:137] op_sel_hi:[1,0]
	v_cvt_pk_bf16_f32 v132, v132, v133
	v_cvt_pk_bf16_f32 v133, v134, v135
	v_cvt_pk_bf16_f32 v134, v140, v141
	v_cvt_pk_bf16_f32 v135, v138, v139
	global_store_dwordx4 v[128:129], v[132:135], off
	v_pk_mul_f32 v[138:139], v[90:91], v[136:137] op_sel_hi:[1,0]
	s_nop 0
	v_pk_mul_f32 v[134:135], v[94:95], v[136:137] op_sel_hi:[1,0]
	v_pk_mul_f32 v[132:133], v[92:93], v[136:137] op_sel_hi:[1,0]
	v_pk_mul_f32 v[136:137], v[88:89], v[136:137] op_sel_hi:[1,0]
	v_cvt_pk_bf16_f32 v132, v132, v133
	v_cvt_pk_bf16_f32 v133, v134, v135
	v_cvt_pk_bf16_f32 v134, v136, v137
	v_cvt_pk_bf16_f32 v135, v138, v139
	global_store_dwordx4 v[128:129], v[132:135], off offset:256
	v_add_u32_e32 v128, 0x90, v166
	v_ashrrev_i32_e32 v129, 31, v128
	v_lshlrev_b64 v[132:133], 6, v[128:129]
	v_lshl_add_u64 v[132:133], v[160:161], 0, v[132:133]
	s_nop 0
	v_lshlrev_b64 v[128:129], 10, v[128:129]
	v_lshl_add_u64 v[128:129], s[10:11], 0, v[128:129]
	v_lshl_add_u64 v[128:129], v[128:129], 0, v[192:193]
	s_waitcnt lgkmcnt(0)
	s_nop 3
	s_nop 0
	s_nop 1
	s_waitcnt lgkmcnt(0)
	s_nop 1
	s_waitcnt lgkmcnt(0)
	s_nop 1
	v_mov_b32_e32 v136, v240
	s_nop 0
	v_pk_mul_f32 v[134:135], v[22:23], v[136:137] op_sel_hi:[1,0]
	v_pk_mul_f32 v[132:133], v[20:21], v[136:137] op_sel_hi:[1,0]
	v_pk_mul_f32 v[138:139], v[18:19], v[136:137] op_sel_hi:[1,0]
	v_pk_mul_f32 v[140:141], v[16:17], v[136:137] op_sel_hi:[1,0]
	v_cvt_pk_bf16_f32 v132, v132, v133
	v_cvt_pk_bf16_f32 v133, v134, v135
	v_cvt_pk_bf16_f32 v134, v140, v141
	v_cvt_pk_bf16_f32 v135, v138, v139
	global_store_dwordx4 v[128:129], v[132:135], off
	v_pk_mul_f32 v[138:139], v[82:83], v[136:137] op_sel_hi:[1,0]
	s_nop 0
	v_pk_mul_f32 v[134:135], v[86:87], v[136:137] op_sel_hi:[1,0]
	v_pk_mul_f32 v[132:133], v[84:85], v[136:137] op_sel_hi:[1,0]
	v_pk_mul_f32 v[136:137], v[80:81], v[136:137] op_sel_hi:[1,0]
	v_cvt_pk_bf16_f32 v132, v132, v133
	v_cvt_pk_bf16_f32 v133, v134, v135
	v_cvt_pk_bf16_f32 v134, v136, v137
	v_cvt_pk_bf16_f32 v135, v138, v139
	global_store_dwordx4 v[128:129], v[132:135], off offset:256
	v_add_u32_e32 v128, 0xa0, v166
	v_ashrrev_i32_e32 v129, 31, v128
	v_lshlrev_b64 v[132:133], 6, v[128:129]
	v_lshl_add_u64 v[132:133], v[160:161], 0, v[132:133]
	s_nop 0
	v_lshlrev_b64 v[128:129], 10, v[128:129]
	v_lshl_add_u64 v[128:129], s[10:11], 0, v[128:129]
	v_lshl_add_u64 v[128:129], v[128:129], 0, v[192:193]
	s_waitcnt lgkmcnt(0)
	s_nop 3
	s_nop 0
	s_nop 1
	s_waitcnt lgkmcnt(0)
	s_nop 1
	s_waitcnt lgkmcnt(0)
	s_nop 1
	v_mov_b32_e32 v136, v241
	s_nop 0
	v_pk_mul_f32 v[134:135], v[14:15], v[136:137] op_sel_hi:[1,0]
	v_pk_mul_f32 v[132:133], v[12:13], v[136:137] op_sel_hi:[1,0]
	v_pk_mul_f32 v[138:139], v[10:11], v[136:137] op_sel_hi:[1,0]
	v_pk_mul_f32 v[140:141], v[8:9], v[136:137] op_sel_hi:[1,0]
	v_cvt_pk_bf16_f32 v132, v132, v133
	v_cvt_pk_bf16_f32 v133, v134, v135
	v_cvt_pk_bf16_f32 v134, v140, v141
	v_cvt_pk_bf16_f32 v135, v138, v139
	global_store_dwordx4 v[128:129], v[132:135], off
	v_pk_mul_f32 v[138:139], v[74:75], v[136:137] op_sel_hi:[1,0]
	s_nop 0
	v_pk_mul_f32 v[134:135], v[78:79], v[136:137] op_sel_hi:[1,0]
	v_pk_mul_f32 v[132:133], v[76:77], v[136:137] op_sel_hi:[1,0]
	v_pk_mul_f32 v[136:137], v[72:73], v[136:137] op_sel_hi:[1,0]
	v_cvt_pk_bf16_f32 v132, v132, v133
	v_cvt_pk_bf16_f32 v133, v134, v135
	v_cvt_pk_bf16_f32 v134, v136, v137
	v_cvt_pk_bf16_f32 v135, v138, v139
	global_store_dwordx4 v[128:129], v[132:135], off offset:256
	v_add_u32_e32 v128, 0xb0, v166
	v_ashrrev_i32_e32 v129, 31, v128
	v_lshlrev_b64 v[132:133], 6, v[128:129]
	v_lshl_add_u64 v[132:133], v[160:161], 0, v[132:133]
	s_nop 0
	v_lshlrev_b64 v[128:129], 10, v[128:129]
	s_waitcnt lgkmcnt(0)
	s_nop 3
	v_lshl_add_u64 v[134:135], s[10:11], 0, v[128:129]
	s_nop 1
	v_lshl_add_u64 v[134:135], v[134:135], 0, v[192:193]
	s_mov_b64 s[10:11], 0
	s_waitcnt lgkmcnt(0)
	s_nop 1
	s_waitcnt lgkmcnt(0)
	s_nop 1
	v_mov_b32_e32 v132, v245
	s_nop 0
	v_pk_mul_f32 v[130:131], v[6:7], v[132:133] op_sel_hi:[1,0]
	v_pk_mul_f32 v[128:129], v[4:5], v[132:133] op_sel_hi:[1,0]
	v_pk_mul_f32 v[136:137], v[2:3], v[132:133] op_sel_hi:[1,0]
	v_pk_mul_f32 v[138:139], v[0:1], v[132:133] op_sel_hi:[1,0]
	v_cvt_pk_bf16_f32 v128, v128, v129
	v_cvt_pk_bf16_f32 v129, v130, v131
	v_cvt_pk_bf16_f32 v130, v138, v139
	v_cvt_pk_bf16_f32 v131, v136, v137
	global_store_dwordx4 v[134:135], v[128:131], off
	v_pk_mul_f32 v[136:137], v[66:67], v[132:133] op_sel_hi:[1,0]
	s_nop 0
	v_pk_mul_f32 v[130:131], v[70:71], v[132:133] op_sel_hi:[1,0]
	v_pk_mul_f32 v[128:129], v[68:69], v[132:133] op_sel_hi:[1,0]
	v_pk_mul_f32 v[132:133], v[64:65], v[132:133] op_sel_hi:[1,0]
	v_cvt_pk_bf16_f32 v128, v128, v129
	v_cvt_pk_bf16_f32 v129, v130, v131
	v_cvt_pk_bf16_f32 v130, v132, v133
	v_cvt_pk_bf16_f32 v131, v136, v137
	global_store_dwordx4 v[134:135], v[128:131], off offset:256
